# diff-latent loop: whole tile as one MFMA stream, loop-top (LDS staging writes, address math, prefetch) moved into MFMA gaps, 4 LDS read buffers
# speedup vs baseline: 1.0197x; 1.0060x over previous
.LBB0_928:
	s_and_b32 s48, s46, 1
	s_mul_i32 s6, s47, 0x4800
	v_add_u32_e32 v69, s6, v175
	s_mul_i32 s6, s48, 0x4400
	v_add_u32_e32 v68, s6, v171
	ds_read_b128 v[72:75], v68
	ds_read_b128 v[76:79], v68 offset:8704
	ds_read_b128 v[222:225], v68 offset:32
	ds_read_b128 v[226:229], v68 offset:8736
	s_xor_b32 s6, s48, 1
	s_mulk_i32 s6, 0x4400
	s_mul_i32 s7, s45, 0x4800
	v_add_u32_e32 v64, s7, v199
	v_add3_u32 v65, s6, v202, v203
	v_add3_u32 v70, s6, v220, v221
	s_cmp_lt_u32 s46, 62
	s_cbranch_scc1 .LBB0_930
	s_sub_i32 s40, s46, 62
	s_lshl_b64 s[6:7], s[40:41], 16
	s_add_u32 s6, s33, s6
	s_addc_u32 s7, s42, s7
	s_lshl_b64 s[8:9], s[40:41], 7
	s_add_u32 s22, s43, s8
	s_addc_u32 s23, s44, s9
	s_mov_b64 s[20:21], 0x200
	s_mov_b64 s[8:9], 0x200
	s_branch .LBB0_931

.LBB0_931:
	s_waitcnt lgkmcnt(3)
	v_mfma_f32_32x32x16_bf16 v[112:127], v[72:75], v[140:143], v[80:95]
	ds_read_b128 v[72:75], v68 offset:64
	v_add_u32_e32 v71, v64, v201
	s_waitcnt vmcnt(0)
	ds_write_b128 v65, v[156:159]
	v_add_u32_e32 v71, 0x8800, v71
	s_waitcnt lgkmcnt(4)
	v_mfma_f32_32x32x16_bf16 v[240:255], v[76:79], v[140:143], v[80:95]
	ds_read_b128 v[76:79], v68 offset:8768
	v_add_u32_e32 v64, v64, v219
	ds_write2_b64 v71, v[148:149], v[150:151] offset1:2
	v_add_u32_e32 v64, 0x8800, v64
	s_waitcnt lgkmcnt(5)
	v_mfma_f32_32x32x16_bf16 v[112:127], v[222:225], v[136:139], v[112:127]
	ds_read_b128 v[222:225], v68 offset:96
	ds_write_b128 v70, v[152:155]
	ds_write2_b64 v64, v[144:145], v[146:147] offset1:2
	s_waitcnt lgkmcnt(7)
	v_mfma_f32_32x32x16_bf16 v[240:255], v[226:229], v[136:139], v[240:255]
	ds_read_b128 v[226:229], v68 offset:8800
	v_lshl_add_u64 v[64:65], s[22:23], 0, v[192:193]
	v_mad_i64_i32 v[66:67], s[22:23], s20, v197, 0
	s_waitcnt lgkmcnt(7)
	v_mfma_f32_32x32x16_bf16 v[112:127], v[72:75], v[132:135], v[112:127]
	ds_read_b128 v[72:75], v69 offset:34816
	v_lshl_add_u64 v[66:67], v[66:67], 1, s[6:7]
	v_lshl_add_u64 v[66:67], v[168:169], 1, v[66:67]
	global_load_dwordx4 v[156:159], v[66:67], off
	s_waitcnt lgkmcnt(6)
	v_mfma_f32_32x32x16_bf16 v[240:255], v[76:79], v[132:135], v[240:255]
	ds_read_b128 v[76:79], v69 offset:34848
	v_mad_i64_i32 v[66:67], s[22:23], s8, v170, 0
	v_lshl_add_u64 v[66:67], v[66:67], 1, v[64:65]
	global_load_dwordx4 v[148:151], v[66:67], off
	s_waitcnt lgkmcnt(5)
	v_mfma_f32_32x32x16_bf16 v[112:127], v[222:225], v[128:131], v[112:127]
	ds_read_b128 v[222:225], v69 offset:34880
	v_mad_i64_i32 v[66:67], s[20:21], s20, v198, 0
	v_lshl_add_u64 v[66:67], v[66:67], 1, s[6:7]
	s_waitcnt lgkmcnt(3)
	v_mfma_f32_32x32x16_bf16 v[240:255], v[226:229], v[128:131], v[240:255]
	ds_read_b128 v[226:229], v69 offset:34912
	v_lshl_add_u64 v[66:67], v[172:173], 1, v[66:67]
	global_load_dwordx4 v[152:155], v[66:67], off
	s_waitcnt lgkmcnt(3)
	v_mfma_f32_32x32x16_bf16 v[48:63], v[72:75], v[104:107], v[48:63]
	ds_read_b128 v[72:75], v69 offset:39424
	v_mad_i64_i32 v[66:67], s[6:7], s8, v174, 0
	v_lshl_add_u64 v[64:65], v[66:67], 1, v[64:65]
	global_load_dwordx4 v[144:147], v[64:65], off
	s_waitcnt lgkmcnt(3)
	v_mfma_f32_32x32x16_bf16 v[48:63], v[76:79], v[108:111], v[48:63]
	ds_read_b128 v[76:79], v69 offset:39456
	s_mov_b64 s[8:9], 0
	s_waitcnt lgkmcnt(3)
	v_mfma_f32_32x32x16_bf16 v[48:63], v[222:225], v[96:99], v[48:63]
	ds_read_b128 v[222:225], v69 offset:39488
	s_mov_b32 s6, 0x40c00000
	s_waitcnt lgkmcnt(3)
	v_mfma_f32_32x32x16_bf16 v[48:63], v[226:229], v[100:103], v[48:63]
	ds_read_b128 v[226:229], v69 offset:39520
	v_max_f32_e32 v70, v113, v113
	v_max_f32_e32 v71, v112, v112
	v_max_f32_e32 v70, v71, v70
	v_max3_f32 v64, v114, v115, v241
	v_max3_f32 v65, v70, v240, v242
	s_waitcnt lgkmcnt(3)
	v_mfma_f32_32x32x16_bf16 v[32:47], v[72:75], v[104:107], v[32:47]
	ds_read_b128 v[72:75], v69 offset:44032
	v_max3_f32 v65, v65, v243, v116
	v_max3_f32 v64, v64, v118, v119
	v_max3_f32 v65, v65, v117, v244
	v_max3_f32 v64, v64, v246, v247
	v_max3_f32 v65, v65, v245, v120
	s_waitcnt lgkmcnt(3)
	v_mfma_f32_32x32x16_bf16 v[32:47], v[76:79], v[108:111], v[32:47]
	ds_read_b128 v[76:79], v69 offset:44064
	v_max3_f32 v64, v64, v122, v123
	v_max3_f32 v65, v65, v121, v248
	v_max3_f32 v64, v64, v250, v251
	v_max3_f32 v65, v65, v249, v124
	v_max3_f32 v64, v64, v126, v127
	s_waitcnt lgkmcnt(3)
	v_mfma_f32_32x32x16_bf16 v[32:47], v[222:225], v[96:99], v[32:47]
	ds_read_b128 v[222:225], v69 offset:44096
	v_max3_f32 v65, v65, v125, v252
	v_max3_f32 v64, v64, v254, v255
	v_max3_f32 v64, v65, v253, v64
	v_mov_b32_e32 v65, v64
	s_waitcnt lgkmcnt(3)
	v_mfma_f32_32x32x16_bf16 v[32:47], v[226:229], v[100:103], v[32:47]
	ds_read_b128 v[226:229], v69 offset:44128
	v_permlane32_swap_b32_e32 v64, v65
	v_max_f32_e32 v65, v65, v65
	v_max_f32_e32 v64, v64, v64
	v_max_f32_e32 v64, v64, v65
	v_cmp_lt_f32_e32 vcc, s6, v64
	s_cbranch_vccnz .Ldl_rare
	s_waitcnt lgkmcnt(3)
	v_mfma_f32_32x32x16_bf16 v[16:31], v[72:75], v[104:107], v[16:31]
	ds_read_b128 v[72:75], v69 offset:48640
	v_exp_f32_e32 v112, v112
	v_exp_f32_e32 v113, v113
	v_exp_f32_e32 v176, v240
	s_waitcnt lgkmcnt(3)
	v_mfma_f32_32x32x16_bf16 v[16:31], v[76:79], v[108:111], v[16:31]
	ds_read_b128 v[76:79], v69 offset:48672
	v_exp_f32_e32 v177, v241
	v_exp_f32_e32 v114, v114
	v_exp_f32_e32 v115, v115
	s_waitcnt lgkmcnt(3)
	v_mfma_f32_32x32x16_bf16 v[16:31], v[222:225], v[96:99], v[16:31]
	ds_read_b128 v[222:225], v69 offset:48704
	v_exp_f32_e32 v178, v242
	v_exp_f32_e32 v179, v243
	v_exp_f32_e32 v116, v116
	s_waitcnt lgkmcnt(3)
	v_mfma_f32_32x32x16_bf16 v[16:31], v[226:229], v[100:103], v[16:31]
	ds_read_b128 v[226:229], v69 offset:48736
	v_exp_f32_e32 v117, v117
	v_exp_f32_e32 v180, v244
	v_exp_f32_e32 v181, v245
	s_waitcnt lgkmcnt(3)
	v_mfma_f32_32x32x16_bf16 v[0:15], v[72:75], v[104:107], v[0:15]
	v_exp_f32_e32 v118, v118
	v_exp_f32_e32 v119, v119
	v_exp_f32_e32 v182, v246
	s_waitcnt lgkmcnt(2)
	v_mfma_f32_32x32x16_bf16 v[0:15], v[76:79], v[108:111], v[0:15]
	v_exp_f32_e32 v183, v247
	v_exp_f32_e32 v120, v120
	v_exp_f32_e32 v121, v121
	s_waitcnt lgkmcnt(1)
	v_mfma_f32_32x32x16_bf16 v[0:15], v[222:225], v[96:99], v[0:15]
	v_exp_f32_e32 v184, v248
	v_exp_f32_e32 v185, v249
	v_exp_f32_e32 v122, v122
	s_waitcnt lgkmcnt(0)
	v_mfma_f32_32x32x16_bf16 v[0:15], v[226:229], v[100:103], v[0:15]
	v_exp_f32_e32 v123, v123
	v_exp_f32_e32 v186, v250
	v_exp_f32_e32 v187, v251
	v_exp_f32_e32 v124, v124
	v_exp_f32_e32 v125, v125
	v_exp_f32_e32 v188, v252
	v_exp_f32_e32 v189, v253
	v_exp_f32_e32 v126, v126
	v_exp_f32_e32 v127, v127
	v_exp_f32_e32 v190, v254
	v_exp_f32_e32 v191, v255
.Ldl_join:
	v_cvt_pk_bf16_f32 v104, v112, v113
	v_cvt_pk_bf16_f32 v105, v114, v115
	v_cvt_pk_bf16_f32 v106, v116, v117
	v_cvt_pk_bf16_f32 v107, v118, v119
	v_cvt_pk_bf16_f32 v96, v176, v177
	v_cvt_pk_bf16_f32 v97, v178, v179
	v_cvt_pk_bf16_f32 v98, v180, v181
	v_cvt_pk_bf16_f32 v99, v182, v183
	v_cvt_pk_bf16_f32 v108, v120, v121
	v_cvt_pk_bf16_f32 v109, v122, v123
	v_cvt_pk_bf16_f32 v110, v124, v125
	v_cvt_pk_bf16_f32 v111, v126, v127
	v_cvt_pk_bf16_f32 v100, v184, v185
	v_cvt_pk_bf16_f32 v101, v186, v187
	v_cvt_pk_bf16_f32 v102, v188, v189
	v_cvt_pk_bf16_f32 v103, v190, v191
	s_mov_b64 s[6:7], -1
	v_pk_add_f32 v[112:113], v[114:115], v[112:113]
	v_pk_add_f32 v[114:115], v[178:179], v[176:177]
	v_pk_add_f32 v[112:113], v[116:117], v[112:113]
	v_pk_add_f32 v[114:115], v[180:181], v[114:115]
	v_pk_add_f32 v[112:113], v[118:119], v[112:113]
	v_pk_add_f32 v[114:115], v[182:183], v[114:115]
	v_pk_add_f32 v[112:113], v[120:121], v[112:113]
	v_pk_add_f32 v[114:115], v[184:185], v[114:115]
	s_add_i32 s46, s46, 1
	s_add_i32 s20, s45, 1
	v_pk_add_f32 v[112:113], v[122:123], v[112:113]
	v_pk_add_f32 v[114:115], v[186:187], v[114:115]
	s_cmp_lg_u32 s20, 3
	v_pk_add_f32 v[112:113], v[124:125], v[112:113]
	v_pk_add_f32 v[114:115], v[188:189], v[114:115]
	s_cselect_b32 s20, s20, 0
	s_add_u32 s16, s16, 0x80
	v_pk_add_f32 v[112:113], v[126:127], v[112:113]
	v_pk_add_f32 v[114:115], v[190:191], v[114:115]
	s_addc_u32 s17, s17, 0
	v_pk_add_f32 v[112:113], v[114:115], v[112:113]
	s_add_u32 s18, s18, 0x82000
	s_waitcnt lgkmcnt(0)
	s_barrier
	v_add_f32_e32 v112, v112, v113
	s_addc_u32 s19, s19, 0
	v_add_f32_e32 v166, v166, v112
	s_cmpk_eq_i32 s46, 0x46
	s_cbranch_scc1 .LBB0_940
	s_mov_b32 s47, s3
	s_mov_b32 s3, s45
	s_mov_b32 s45, s20
	s_branch .LBB0_928
.Ldl_rare:
	s_waitcnt lgkmcnt(3)
	v_mfma_f32_32x32x16_bf16 v[16:31], v[72:75], v[104:107], v[16:31]
	ds_read_b128 v[72:75], v69 offset:48640
	s_waitcnt lgkmcnt(3)
	v_mfma_f32_32x32x16_bf16 v[16:31], v[76:79], v[108:111], v[16:31]
	ds_read_b128 v[76:79], v69 offset:48672
	s_waitcnt lgkmcnt(3)
	v_mfma_f32_32x32x16_bf16 v[16:31], v[222:225], v[96:99], v[16:31]
	ds_read_b128 v[222:225], v69 offset:48704
	s_waitcnt lgkmcnt(3)
	v_mfma_f32_32x32x16_bf16 v[16:31], v[226:229], v[100:103], v[16:31]
	ds_read_b128 v[226:229], v69 offset:48736
	s_waitcnt lgkmcnt(3)
	v_mfma_f32_32x32x16_bf16 v[0:15], v[72:75], v[104:107], v[0:15]
	s_waitcnt lgkmcnt(2)
	v_mfma_f32_32x32x16_bf16 v[0:15], v[76:79], v[108:111], v[0:15]
	s_waitcnt lgkmcnt(1)
	v_mfma_f32_32x32x16_bf16 v[0:15], v[222:225], v[96:99], v[0:15]
	s_waitcnt lgkmcnt(0)
	v_mfma_f32_32x32x16_bf16 v[0:15], v[226:229], v[100:103], v[0:15]
	v_max_f32_e32 v64, v64, v64
	v_max_f32_e32 v64, 0, v64
	v_exp_f32_e64 v66, -v64
	v_mov_b32_e32 v67, v64
	v_pk_add_f32 v[112:113], v[112:113], v[64:65] op_sel_hi:[1,0] neg_lo:[0,1] neg_hi:[0,1]
	v_pk_add_f32 v[240:241], v[240:241], v[64:65] op_sel_hi:[1,0] neg_lo:[0,1] neg_hi:[0,1]
	v_pk_add_f32 v[114:115], v[114:115], v[64:65] op_sel_hi:[1,0] neg_lo:[0,1] neg_hi:[0,1]
	v_pk_add_f32 v[242:243], v[242:243], v[64:65] op_sel_hi:[1,0] neg_lo:[0,1] neg_hi:[0,1]
	v_pk_add_f32 v[116:117], v[116:117], v[64:65] op_sel_hi:[1,0] neg_lo:[0,1] neg_hi:[0,1]
	v_pk_add_f32 v[244:245], v[244:245], v[64:65] op_sel_hi:[1,0] neg_lo:[0,1] neg_hi:[0,1]
	v_pk_add_f32 v[118:119], v[118:119], v[64:65] op_sel_hi:[1,0] neg_lo:[0,1] neg_hi:[0,1]
	v_pk_add_f32 v[246:247], v[246:247], v[64:65] op_sel_hi:[1,0] neg_lo:[0,1] neg_hi:[0,1]
	v_pk_add_f32 v[120:121], v[120:121], v[64:65] op_sel_hi:[1,0] neg_lo:[0,1] neg_hi:[0,1]
	v_pk_add_f32 v[248:249], v[248:249], v[64:65] op_sel_hi:[1,0] neg_lo:[0,1] neg_hi:[0,1]
	v_pk_add_f32 v[122:123], v[122:123], v[64:65] op_sel_hi:[1,0] neg_lo:[0,1] neg_hi:[0,1]
	v_pk_add_f32 v[250:251], v[250:251], v[64:65] op_sel_hi:[1,0] neg_lo:[0,1] neg_hi:[0,1]
	v_pk_add_f32 v[124:125], v[124:125], v[64:65] op_sel_hi:[1,0] neg_lo:[0,1] neg_hi:[0,1]
	v_pk_add_f32 v[252:253], v[252:253], v[64:65] op_sel_hi:[1,0] neg_lo:[0,1] neg_hi:[0,1]
	v_pk_add_f32 v[126:127], v[126:127], v[64:65] op_sel_hi:[1,0] neg_lo:[0,1] neg_hi:[0,1]
	v_pk_add_f32 v[254:255], v[254:255], v[64:65] op_sel_hi:[1,0] neg_lo:[0,1] neg_hi:[0,1]
	v_pk_add_f32 v[64:65], v[166:167], v[66:67]
	v_pk_mul_f32 v[166:167], v[166:167], v[66:67]
	v_xor_b32_e32 v64, 0x80000000, v65
	v_mov_b32_e32 v167, v65
	v_pk_mul_f32 v[62:63], v[62:63], v[66:67] op_sel_hi:[1,0]
	v_pk_mul_f32 v[60:61], v[60:61], v[66:67] op_sel_hi:[1,0]
	v_pk_mul_f32 v[58:59], v[58:59], v[66:67] op_sel_hi:[1,0]
	v_pk_mul_f32 v[56:57], v[56:57], v[66:67] op_sel_hi:[1,0]
	v_pk_mul_f32 v[54:55], v[54:55], v[66:67] op_sel_hi:[1,0]
	v_pk_mul_f32 v[52:53], v[52:53], v[66:67] op_sel_hi:[1,0]
	v_pk_mul_f32 v[50:51], v[50:51], v[66:67] op_sel_hi:[1,0]
	v_pk_mul_f32 v[48:49], v[48:49], v[66:67] op_sel_hi:[1,0]
	v_pk_mul_f32 v[46:47], v[46:47], v[66:67] op_sel_hi:[1,0]
	v_pk_mul_f32 v[44:45], v[44:45], v[66:67] op_sel_hi:[1,0]
	v_pk_mul_f32 v[42:43], v[42:43], v[66:67] op_sel_hi:[1,0]
	v_pk_mul_f32 v[40:41], v[40:41], v[66:67] op_sel_hi:[1,0]
	v_pk_mul_f32 v[38:39], v[38:39], v[66:67] op_sel_hi:[1,0]
	v_pk_mul_f32 v[36:37], v[36:37], v[66:67] op_sel_hi:[1,0]
	v_pk_mul_f32 v[34:35], v[34:35], v[66:67] op_sel_hi:[1,0]
	v_pk_mul_f32 v[32:33], v[32:33], v[66:67] op_sel_hi:[1,0]
	v_pk_mul_f32 v[30:31], v[30:31], v[66:67] op_sel_hi:[1,0]
	v_pk_mul_f32 v[28:29], v[28:29], v[66:67] op_sel_hi:[1,0]
	v_pk_mul_f32 v[26:27], v[26:27], v[66:67] op_sel_hi:[1,0]
	v_pk_mul_f32 v[24:25], v[24:25], v[66:67] op_sel_hi:[1,0]
	v_pk_mul_f32 v[22:23], v[22:23], v[66:67] op_sel_hi:[1,0]
	v_pk_mul_f32 v[20:21], v[20:21], v[66:67] op_sel_hi:[1,0]
	v_pk_mul_f32 v[18:19], v[18:19], v[66:67] op_sel_hi:[1,0]
	v_pk_mul_f32 v[16:17], v[16:17], v[66:67] op_sel_hi:[1,0]
	v_pk_mul_f32 v[14:15], v[14:15], v[66:67] op_sel_hi:[1,0]
	v_pk_mul_f32 v[12:13], v[12:13], v[66:67] op_sel_hi:[1,0]
	v_pk_mul_f32 v[10:11], v[10:11], v[66:67] op_sel_hi:[1,0]
	v_pk_mul_f32 v[8:9], v[8:9], v[66:67] op_sel_hi:[1,0]
	v_pk_mul_f32 v[6:7], v[6:7], v[66:67] op_sel_hi:[1,0]
	v_pk_mul_f32 v[4:5], v[4:5], v[66:67] op_sel_hi:[1,0]
	v_pk_mul_f32 v[2:3], v[2:3], v[66:67] op_sel_hi:[1,0]
	v_pk_mul_f32 v[0:1], v[0:1], v[66:67] op_sel_hi:[1,0]
	v_mov_b32_e32 v80, v64
	v_mov_b32_e32 v81, v64
	v_mov_b32_e32 v82, v64
	v_mov_b32_e32 v83, v64
	v_mov_b32_e32 v84, v64
	v_mov_b32_e32 v85, v64
	v_mov_b32_e32 v86, v64
	v_mov_b32_e32 v87, v64
	v_mov_b32_e32 v88, v64
	v_mov_b32_e32 v89, v64
	v_mov_b32_e32 v90, v64
	v_mov_b32_e32 v91, v64
	v_mov_b32_e32 v92, v64
	v_mov_b32_e32 v93, v64
	v_mov_b32_e32 v94, v64
	v_mov_b32_e32 v95, v64
	v_exp_f32_e32 v112, v112
	v_exp_f32_e32 v113, v113
	v_exp_f32_e32 v176, v240
	v_exp_f32_e32 v177, v241
	v_exp_f32_e32 v114, v114
	v_exp_f32_e32 v115, v115
	v_exp_f32_e32 v178, v242
	v_exp_f32_e32 v179, v243
	v_exp_f32_e32 v116, v116
	v_exp_f32_e32 v117, v117
	v_exp_f32_e32 v180, v244
	v_exp_f32_e32 v181, v245
	v_exp_f32_e32 v118, v118
	v_exp_f32_e32 v119, v119
	v_exp_f32_e32 v182, v246
	v_exp_f32_e32 v183, v247
	v_exp_f32_e32 v120, v120
	v_exp_f32_e32 v121, v121
	v_exp_f32_e32 v184, v248
	v_exp_f32_e32 v185, v249
	v_exp_f32_e32 v122, v122
	v_exp_f32_e32 v123, v123
	v_exp_f32_e32 v186, v250
	v_exp_f32_e32 v187, v251
	v_exp_f32_e32 v124, v124
	v_exp_f32_e32 v125, v125
	v_exp_f32_e32 v188, v252
	v_exp_f32_e32 v189, v253
	v_exp_f32_e32 v126, v126
	v_exp_f32_e32 v127, v127
	v_exp_f32_e32 v190, v254
	v_exp_f32_e32 v191, v255
	s_branch .Ldl_join
